# v39 plus LDS fragment address adds hoisted out of the post-barrier segment heads in the attention loop
# speedup vs baseline: 1.0029x; 1.0015x over previous
; __device__ __forceinline__ int otid() { int t = threadIdx.x; asm volatile("" : "+v"(t)); return t; }
; #define WAIT_BAR(N) asm volatile("s_waitcnt vmcnt(" #N ") lgkmcnt(0)\n\ts_barrier":::"memory")
;   #define DMA_K(t,slot) glds16(ksrc+(long)(t)*KVBLK*KVP,(unsigned)__builtin_amdgcn_readfirstlane(kdst+(slot)))
;   #define DMA_V(t,slot) glds16(vsrc+(long)(t)*KVBLK*KVP,(unsigned)__builtin_amdgcn_readfirstlane(vdst+(slot)))
;   #define CMASK(P0,P1,t) do{}while(0)
;   #define CMASK(P0,P1,t) do{}while(0)
;   #define CMASK(P0,P1,t) do{}while(0)
; template<int THRL> __device__ __forceinline__ void attn_unit(const bf16*Qu,const bf16*__restrict__ Kh,const bf16*__restrict__ Vh,bf16*Ou,const int NT,const float shift,char*shm){
;   const int tid=otid(),lane=tid&63,r32=lane&31,hi=lane>>5; const int wid=__builtin_amdgcn_readfirstlane(tid>>6);
;   const bf16*Qw=Qu+(long)wid*QBLK*QP;
;   const unsigned lds0=(unsigned)(uintptr_t)shm;
;   float*wsf=(float*)(shm+LDS_WS)+wid*64;
;   const bf16*ksrc=Kh+(long)lane*KVP+wid*8;
;   const bf16*vsrc=Vh+(long)(16*(wid&3)+(lane>>2))*KVP+(wid>>2)*32+(lane&3)*8;
;   const unsigned kdst=lds0+LDS_K+wid*1024, vdst=lds0+LDS_V+wid*1024;
;     ...
;   const int vb0=(int)(lds0+LDS_V)+((lane>>4)&1)*32+(lane&3)*8+(4*hi+((lane&15)>>2))*64;
;   const char*Kbase=shm+LDS_K; bf16x8 kf[8];
;   const lds_cptr shm3=(lds_cptr)shm; const lds_cptr kp0=shm3+LDS_K+hi*1024+r32*16; const lds_cptr vp0=shm3+LDS_V+((lane>>4)&1)*32+(lane&3)*8+(4*hi+((lane&15)>>2))*64;
;   DMA_K(0,0);DMA_V(0,0);DMA_K(1,SLOTB);
;   bf16x8 qr[4];
;   #pragma unroll
;   for(int d0=0;d0<4;++d0)qr[d0]=*reinterpret_cast<const bf16x8*>(&Qw[(long)r32*QP+d0*16+hi*8]);
;   float mhat=0.f,l_reg=0.f;f32x16 o[2];o[0]=f32x16{};o[1]=f32x16{};f32x16 negm=f32x16{};asm volatile("":"+v"(negm));
;     ...
;   bool resc=false;
;     ...
;   f32x16 pA0,pA1,pB0,pB1;
;   int sl_prev=0,sl_cur=0,sl_next=SLOTB;
;     ...
;   DMA_K(2,2*SLOTB);
;   WAIT_BAR(3);
;   qkt(pA0,pA1,Kbase,qr,negm,r32,hi);asm volatile("s_nop 15\n\ts_nop 7":"+v"(pA0),"+v"(pA1));CMASK(pA0,pA1,0);
;   START(pA0,pA1);
;   _Pragma("unroll") for(int r=0;r<16;++r)pA1[r]=__builtin_amdgcn_exp2f(pA1[r]);
;   WAIT_BAR(0);
.LBB0_616:
	s_lshl_b32 s4, s84, 1
	s_ashr_i32 s5, s82, 2
	s_add_i32 s6, s4, s5
	v_readlane_b32 s4, v246, 62
	v_readlane_b32 s5, v246, 63
	s_lshl_b64 s[4:5], s[4:5], 11
	s_add_u32 s7, s57, s4
	s_addc_u32 s24, s58, s5
	s_lshl_b32 s4, s82, 6
	s_ashr_i32 s5, s4, 31
	s_lshl_b64 s[48:49], s[4:5], 1
	s_add_u32 s26, s7, s48
	s_addc_u32 s27, s24, s49
	s_mul_hi_i32 s7, s6, 0x208000
	s_mul_i32 s6, s6, 0x208000
	s_add_u32 s4, s59, s6
	s_addc_u32 s5, s60, s7
	v_mov_b32_e32 v42, v216
	s_add_u32 s6, s61, s6
	s_addc_u32 s7, s62, s7
	v_readfirstlane_b32 s69, v42
	s_ashr_i32 s44, s69, 6
	s_ashr_i32 s45, s44, 31
	v_and_b32_e32 v238, 63, v42
	s_lshl_b64 s[24:25], s[44:45], 16
	s_add_u32 s24, s26, s24
	v_lshlrev_b32_e32 v0, 4, v42
	s_addc_u32 s25, s27, s25
	v_lshl_add_u64 v[2:3], s[4:5], 0, v[0:1]
	s_mov_b32 s4, 0
	s_ashr_i32 s5, s4, 31
	v_lshl_add_u64 v[212:213], s[4:5], 1, v[2:3]
	s_lshl_b32 s4, s44, 4
	v_bfe_u32 v0, v42, 2, 4
	v_and_or_b32 v0, s4, 48, v0
	s_ashr_i32 s4, s69, 3
	s_andn2_b32 s4, s4, 31
	v_lshlrev_b32_e32 v0, 7, v0
	s_ashr_i32 s5, s4, 31
	s_lshl_b32 s70, s44, 10
	v_lshl_add_u64 v[2:3], s[6:7], 0, v[0:1]
	v_lshlrev_b32_e32 v239, 3, v42
	s_cmp_lg_u32 0, -1
	v_lshl_add_u64 v[2:3], s[4:5], 1, v[2:3]
	v_and_b32_e32 v242, 24, v239
	s_cselect_b32 s4, 0, 0
	v_and_b32_e32 v240, 31, v42
	v_lshlrev_b32_e32 v0, 4, v42
	s_add_i32 s70, s70, s4
	s_mov_b32 s4, m0
	s_mov_b32 m0, s70
	s_nop 0
	global_load_lds_dwordx4 v[212:213], off
	s_mov_b32 m0, s4
	v_bfe_u32 v241, v42, 5, 1
	v_lshl_add_u64 v[214:215], s[6:7], 0, v[0:1]
	s_add_i32 s71, s70, 0x6000
	s_mov_b32 s4, m0
	s_mov_b32 m0, s71
	s_nop 0
	global_load_lds_dwordx4 v[214:215], off
	s_mov_b32 m0, s4
	s_mov_b64 s[26:27], 0x2000
	v_lshlrev_b32_e32 v0, 11, v240
	v_lshl_add_u64 v[2:3], v[212:213], 0, s[26:27]
	s_add_i32 s4, s70, 0x2000
	s_mov_b32 s5, m0
	s_mov_b32 m0, s4
	s_nop 0
	global_load_lds_dwordx4 v[2:3], off
	s_mov_b32 m0, s5
	v_lshl_or_b32 v0, v241, 4, v0
	global_load_dwordx4 v[150:153], v0, s[24:25]
	global_load_dwordx4 v[138:141], v0, s[24:25] offset:32
	global_load_dwordx4 v[134:137], v0, s[24:25] offset:64
	global_load_dwordx4 v[130:133], v0, s[24:25] offset:96
	v_mov_b32_e32 v2, v1
	v_mov_b32_e32 v3, v1
	v_mov_b32_e32 v4, v1
	v_mov_b32_e32 v5, v1
	v_mov_b32_e32 v6, v1
	v_mov_b32_e32 v7, v1
	v_mov_b32_e32 v8, v1
	v_mov_b32_e32 v9, v1
	v_mov_b32_e32 v10, v1
	v_mov_b32_e32 v11, v1
	v_mov_b32_e32 v12, v1
	v_mov_b32_e32 v13, v1
	v_mov_b32_e32 v14, v1
	v_mov_b32_e32 v15, v1
	v_lshlrev_b32_e32 v0, 10, v241
	v_lshlrev_b32_e32 v16, 4, v240
	v_add3_u32 v244, 0, v0, v16
	v_mov_b32_e32 v0, v1
	v_mov_b64_e32 v[16:17], v[14:15]
	v_mov_b64_e32 v[14:15], v[12:13]
	v_mov_b64_e32 v[12:13], v[10:11]
	v_mov_b64_e32 v[10:11], v[8:9]
	v_mov_b64_e32 v[8:9], v[6:7]
	v_mov_b64_e32 v[6:7], v[4:5]
	v_mov_b64_e32 v[4:5], v[2:3]
	v_mov_b64_e32 v[2:3], v[0:1]
	v_lshl_add_u64 v[18:19], v[212:213], 0, s[72:73]
	s_add_i32 s4, s70, 0x4000
	s_mov_b32 s5, m0
	s_mov_b32 m0, s4
	s_nop 0
	global_load_lds_dwordx4 v[18:19], off
	s_mov_b32 m0, s5
	s_waitcnt vmcnt(3) lgkmcnt(0)
	s_barrier
	ds_read_b128 v[34:37], v244
	ds_read_b128 v[38:41], v244 offset:512
	v_lshlrev_b32_e32 v0, 1, v42
	v_and_b32_e32 v243, 32, v0
	s_mov_b64 s[34:35], 0x6000
	v_add_u32_e32 v50, 0, v243
	s_mov_b32 s5, 1
	s_mov_b32 s4, 0
	s_movk_i32 s31, 0x2000
	s_mov_b32 s24, 0
	s_movk_i32 s76, 0x4000
	s_waitcnt vmcnt(3) lgkmcnt(1)
	v_mfma_f32_32x32x16_bf16 v[18:33], v[34:37], v[150:153], v[2:17]
	s_waitcnt lgkmcnt(0)
	v_mfma_f32_32x32x16_bf16 v[2:17], v[38:41], v[150:153], v[2:17]
	ds_read_b128 v[34:37], v244 offset:2048
	ds_read_b128 v[38:41], v244 offset:2560
	s_waitcnt vmcnt(2) lgkmcnt(1)
	v_mfma_f32_32x32x16_bf16 v[18:33], v[34:37], v[138:141], v[18:33]
	s_waitcnt lgkmcnt(0)
	v_mfma_f32_32x32x16_bf16 v[2:17], v[38:41], v[138:141], v[2:17]
	ds_read_b128 v[34:37], v244 offset:4096
	ds_read_b128 v[38:41], v244 offset:4608
	s_waitcnt vmcnt(1) lgkmcnt(1)
	v_mfma_f32_32x32x16_bf16 v[18:33], v[34:37], v[134:137], v[18:33]
	ds_read_b128 v[34:37], v244 offset:6144
	s_waitcnt lgkmcnt(1)
	v_mfma_f32_32x32x16_bf16 v[2:17], v[38:41], v[134:137], v[2:17]
	ds_read_b128 v[38:41], v244 offset:6656
	s_waitcnt vmcnt(0) lgkmcnt(1)
	v_mfma_f32_32x32x16_bf16 v[18:33], v[34:37], v[130:133], v[18:33]
	v_add_f32_e32 v34, v1, v237
	v_lshlrev_b32_e32 v35, 4, v42
	v_xor_b32_e32 v34, 0x80000000, v34
	v_and_b32_e32 v0, 0xc0, v35
	v_mov_b32_e32 v35, v34
	v_mov_b32_e32 v36, v34
	v_mov_b32_e32 v37, v34
	s_waitcnt lgkmcnt(0)
	v_mfma_f32_32x32x16_bf16 v[2:17], v[38:41], v[130:133], v[2:17]
	s_nop 15
	s_nop 7
	v_mov_b32_e32 v38, v34
	v_mov_b32_e32 v39, v34
	v_mov_b32_e32 v40, v34
	v_mov_b32_e32 v41, v34
	v_mov_b32_e32 v42, v34
	v_mov_b32_e32 v43, v34
	v_mov_b32_e32 v44, v34
	v_mov_b32_e32 v45, v34
	v_mov_b32_e32 v46, v34
	v_mov_b32_e32 v47, v34
	v_mov_b32_e32 v48, v34
	v_mov_b32_e32 v49, v34
	v_sub_f32_e32 v2, v2, v237
	v_sub_f32_e32 v3, v3, v237
	s_waitcnt vmcnt(0) lgkmcnt(0)
	s_barrier
; #define WAIT_BAR(N) asm volatile("s_waitcnt vmcnt(" #N ") lgkmcnt(0)\n\ts_barrier":::"memory")
;   #define DMA_K(t,slot) glds16(ksrc+(long)(t)*KVBLK*KVP,(unsigned)__builtin_amdgcn_readfirstlane(kdst+(slot)))
;   #define DMA_V(t,slot) glds16(vsrc+(long)(t)*KVBLK*KVP,(unsigned)__builtin_amdgcn_readfirstlane(vdst+(slot)))
;   #define ROT() do{sl_prev=sl_cur;sl_cur=sl_next;sl_next=(sl_next==(NSLOT-1)*SLOTB)?0:sl_next+SLOTB;}while(0)
; template<int THRL> __device__ __forceinline__ void attn_unit(const bf16*Qu,const bf16*__restrict__ Kh,const bf16*__restrict__ Vh,bf16*Ou,const int NT,const float shift,char*shm){
;     ...
;   WAIT_BAR(0);
;   DMA_K(3,0);DMA_V(1,SLOTB);
;   ROT();
;   kload8(kf,kp0+sl_cur);
;   WAIT_BAR(2);
;   s16x4 vlo[8],vhi[8]; u32x4 pw0,pw1,pw2,pw3;
	v_sub_f32_e32 v18, v18, v237
	v_sub_f32_e32 v19, v19, v237
	s_nop 0
	v_exp_f32_e32 v66, v2
	v_exp_f32_e32 v67, v3
	v_lshl_add_u64 v[2:3], v[212:213], 0, s[34:35]
	s_mov_b32 s6, m0
	s_mov_b32 m0, s70
	s_nop 0
	global_load_lds_dwordx4 v[2:3], off
	s_mov_b32 m0, s6
	v_lshl_add_u64 v[2:3], v[214:215], 0, s[26:27]
	s_add_i32 s6, s70, 0x8000
	s_mov_b32 s7, m0
	s_mov_b32 m0, s6
	s_nop 0
	global_load_lds_dwordx4 v[2:3], off
	s_mov_b32 m0, s7
	ds_read_b128 v[190:193], v244 offset:8192
	ds_read_b128 v[186:189], v244 offset:8704
	ds_read_b128 v[182:185], v244 offset:10240
	ds_read_b128 v[178:181], v244 offset:10752
	ds_read_b128 v[174:177], v244 offset:12288
	ds_read_b128 v[170:173], v244 offset:12800
	ds_read_b128 v[166:169], v244 offset:14336
	ds_read_b128 v[162:165], v244 offset:14848
	v_sub_f32_e32 v20, v20, v237
	v_sub_f32_e32 v4, v4, v237
	v_sub_f32_e32 v21, v21, v237
	v_sub_f32_e32 v5, v5, v237
	v_sub_f32_e32 v22, v22, v237
	v_sub_f32_e32 v6, v6, v237
	v_sub_f32_e32 v23, v23, v237
	v_sub_f32_e32 v7, v7, v237
	v_sub_f32_e32 v24, v24, v237
	v_sub_f32_e32 v8, v8, v237
	v_sub_f32_e32 v25, v25, v237
	v_sub_f32_e32 v9, v9, v237
	v_sub_f32_e32 v26, v26, v237
	v_sub_f32_e32 v10, v10, v237
	v_sub_f32_e32 v27, v27, v237
	v_sub_f32_e32 v11, v11, v237
	v_sub_f32_e32 v28, v28, v237
	v_sub_f32_e32 v12, v12, v237
	v_sub_f32_e32 v29, v29, v237
	v_sub_f32_e32 v13, v13, v237
	v_sub_f32_e32 v30, v30, v237
	v_sub_f32_e32 v14, v14, v237
	v_sub_f32_e32 v31, v31, v237
	v_sub_f32_e32 v15, v15, v237
	v_sub_f32_e32 v32, v32, v237
	v_sub_f32_e32 v16, v16, v237
	v_sub_f32_e32 v33, v33, v237
	v_sub_f32_e32 v17, v17, v237
	v_exp_f32_e32 v82, v18
	v_exp_f32_e32 v83, v19
	v_exp_f32_e32 v84, v20
	v_exp_f32_e32 v85, v21
	v_exp_f32_e32 v86, v22
	v_exp_f32_e32 v87, v23
	v_exp_f32_e32 v88, v24
	v_exp_f32_e32 v89, v25
	v_exp_f32_e32 v90, v26
	v_exp_f32_e32 v91, v27
	v_exp_f32_e32 v92, v28
	v_exp_f32_e32 v93, v29
	v_exp_f32_e32 v94, v30
	v_exp_f32_e32 v95, v31
	v_exp_f32_e32 v96, v32
	v_exp_f32_e32 v97, v33
	v_exp_f32_e32 v68, v4
	v_exp_f32_e32 v69, v5
	v_exp_f32_e32 v70, v6
	v_exp_f32_e32 v71, v7
	v_exp_f32_e32 v72, v8
	v_exp_f32_e32 v73, v9
	v_exp_f32_e32 v74, v10
	v_exp_f32_e32 v75, v11
	v_exp_f32_e32 v76, v12
	v_exp_f32_e32 v77, v13
	v_exp_f32_e32 v78, v14
	v_exp_f32_e32 v79, v15
	v_exp_f32_e32 v80, v16
	v_exp_f32_e32 v81, v17
	s_waitcnt vmcnt(2) lgkmcnt(0)
	s_barrier
	v_lshl_or_b32 v0, v241, 8, v0
	v_add3_u32 v245, v50, v242, v0
	s_cmp_lt_i32 s91, 7
	s_cbranch_scc1 .LBB0_620
	s_mov_b64 s[4:5], 0xa000
	v_add_u32_e32 v51, s24, v245
	v_mov_b32_e32 v50, 0
	v_mov_b32_e32 v194, 0
	v_mov_b32_e32 v195, 0
	v_mov_b32_e32 v196, 0
	v_lshlrev_b32_e32 v197, 4, v238
	v_readfirstlane_b32 s98, v212
	v_readfirstlane_b32 s99, v213
	v_readfirstlane_b32 s100, v214
	v_readfirstlane_b32 s101, v215
	s_add_u32 s98, s98, 0x8000
	s_addc_u32 s99, s99, 0
	s_add_u32 s100, s100, 0x4000
	s_addc_u32 s101, s101, 0
	s_mov_b32 s26, 6
	v_mov_b32_e32 v2, 0
	v_mov_b32_e32 v3, v50
	v_mov_b32_e32 v4, v50
	v_mov_b32_e32 v5, v50
	v_mov_b32_e32 v6, v50
	v_mov_b32_e32 v7, v50
	v_mov_b32_e32 v8, v50
	v_mov_b32_e32 v9, v50
	v_mov_b32_e32 v10, v50
	v_mov_b32_e32 v11, v50
	v_mov_b32_e32 v12, v50
	v_mov_b32_e32 v13, v50
	v_mov_b32_e32 v14, v50
	v_mov_b32_e32 v15, v50
	v_mov_b32_e32 v16, v50
	v_mov_b32_e32 v17, v50
	v_mov_b32_e32 v18, 0
	v_mov_b32_e32 v19, v50
	v_mov_b32_e32 v20, v50
	v_mov_b32_e32 v21, v50
	v_mov_b32_e32 v22, v50
	v_mov_b32_e32 v23, v50
	v_mov_b32_e32 v24, v50
	v_mov_b32_e32 v25, v50
	v_mov_b32_e32 v26, v50
	v_mov_b32_e32 v27, v50
	v_mov_b32_e32 v28, v50
	v_mov_b32_e32 v29, v50
	v_mov_b32_e32 v30, v50
	v_mov_b32_e32 v31, v50
	v_mov_b32_e32 v32, v50
	v_mov_b32_e32 v33, v50
.LBB0_618:
	s_mov_b32 s4, s76
	s_mov_b32 s5, s26
	s_mov_b32 s25, s31
	ds_read_b64_tr_b16 v[52:53], v51 offset:24576
	ds_read_b64_tr_b16 v[54:55], v51 offset:25088
	s_waitcnt lgkmcnt(9)
	v_mfma_f32_32x32x16_bf16 v[114:129], v[190:193], v[150:153], v[34:49]
	v_add_f32_e32 v50, v82, v50
	v_add_f32_e32 v194, v83, v194
	v_add_f32_e32 v195, v84, v195
	v_add_f32_e32 v196, v85, v196
	v_add_f32_e32 v50, v86, v50
	v_add_f32_e32 v194, v87, v194
	v_cvt_pk_bf16_f32 v158, v82, v83
	v_cvt_pk_bf16_f32 v159, v84, v85
	ds_read_b64_tr_b16 v[60:61], v51 offset:28672
	ds_read_b64_tr_b16 v[62:63], v51 offset:29184
	s_waitcnt lgkmcnt(10)
	v_mfma_f32_32x32x16_bf16 v[98:113], v[186:189], v[150:153], v[34:49]
	v_add_f32_e32 v195, v88, v195
	v_add_f32_e32 v196, v89, v196
	v_add_f32_e32 v50, v90, v50
	v_add_f32_e32 v194, v91, v194
	v_cvt_pk_bf16_f32 v160, v86, v87
	v_cvt_pk_bf16_f32 v161, v88, v89
	ds_read_b64_tr_b16 v[82:83], v51 offset:25600
	ds_read_b64_tr_b16 v[84:85], v51 offset:26112
	s_waitcnt lgkmcnt(11)
	v_mfma_f32_32x32x16_bf16 v[114:129], v[182:185], v[138:141], v[114:129]
	v_add_f32_e32 v195, v92, v195
	v_add_f32_e32 v196, v93, v196
	v_add_f32_e32 v50, v94, v50
	v_add_f32_e32 v194, v95, v194
	v_cvt_pk_bf16_f32 v154, v90, v91
	v_cvt_pk_bf16_f32 v155, v92, v93
	ds_read_b64_tr_b16 v[86:87], v51 offset:29696
	ds_read_b64_tr_b16 v[88:89], v51 offset:30208
	s_waitcnt lgkmcnt(12)
	v_mfma_f32_32x32x16_bf16 v[98:113], v[178:181], v[138:141], v[98:113]
	v_add_f32_e32 v195, v96, v195
	v_add_f32_e32 v196, v97, v196
	v_add_f32_e32 v50, v66, v50
	v_add_f32_e32 v194, v67, v194
	v_cvt_pk_bf16_f32 v156, v94, v95
	v_cvt_pk_bf16_f32 v157, v96, v97
	ds_read_b64_tr_b16 v[90:91], v51 offset:26624
	ds_read_b64_tr_b16 v[92:93], v51 offset:27136
	s_waitcnt lgkmcnt(13)
	v_mfma_f32_32x32x16_bf16 v[114:129], v[174:177], v[134:137], v[114:129]
	v_add_f32_e32 v195, v68, v195
	v_add_f32_e32 v196, v69, v196
	v_add_f32_e32 v50, v70, v50
	v_add_f32_e32 v194, v71, v194
	v_cvt_pk_bf16_f32 v146, v66, v67
	v_cvt_pk_bf16_f32 v147, v68, v69
	ds_read_b64_tr_b16 v[64:65], v51 offset:30720
	ds_read_b64_tr_b16 v[66:67], v51 offset:31232
	s_waitcnt lgkmcnt(14)
; #define WAIT_BAR(N) asm volatile("s_waitcnt vmcnt(" #N ") lgkmcnt(0)\n\ts_barrier":::"memory")
;   #define RESC() do{ if(resc){ asm volatile("s_waitcnt lgkmcnt(0)":::"memory"); \
;       _Pragma("unroll") for(int d_=0;d_<2;++d_) _Pragma("unroll") for(int r=0;r<16;++r)o[d_][r]*=wsf[crow(r,hi)]; } }while(0)
;   #define ROT() do{sl_prev=sl_cur;sl_cur=sl_next;sl_next=(sl_next==(NSLOT-1)*SLOTB)?0:sl_next+SLOTB;}while(0)
; template<int THRL> __device__ __forceinline__ void attn_unit(const bf16*Qu,const bf16*__restrict__ Kh,const bf16*__restrict__ Vh,bf16*Ou,const int NT,const float shift,char*shm){
;     ...
;   int t=1;
;     ...
;   for(;t+5<NT;t+=2){
;     STEP(pB0,pB1,pA0,pA1,t,true,true,true);     WAIT_BAR(2); RESC(); ROT();
	v_mfma_f32_32x32x16_bf16 v[98:113], v[170:173], v[134:137], v[98:113]
	v_add_f32_e32 v195, v72, v195
	v_add_f32_e32 v196, v73, v196
	v_add_f32_e32 v50, v74, v50
	v_add_f32_e32 v194, v75, v194
	v_cvt_pk_bf16_f32 v148, v70, v71
	v_cvt_pk_bf16_f32 v149, v72, v73
	ds_read_b64_tr_b16 v[68:69], v51 offset:27648
	ds_read_b64_tr_b16 v[70:71], v51 offset:28160
	s_waitcnt lgkmcnt(14)
	v_mfma_f32_32x32x16_bf16 v[114:129], v[166:169], v[130:133], v[114:129]
	v_add_f32_e32 v195, v76, v195
	v_add_f32_e32 v196, v77, v196
	v_add_f32_e32 v50, v78, v50
	v_add_f32_e32 v194, v79, v194
	v_cvt_pk_bf16_f32 v142, v74, v75
	v_cvt_pk_bf16_f32 v143, v76, v77
	ds_read_b64_tr_b16 v[72:73], v51 offset:31744
	ds_read_b64_tr_b16 v[74:75], v51 offset:32256
	v_mfma_f32_32x32x16_bf16 v[98:113], v[162:165], v[130:133], v[98:113]
	v_add_f32_e32 v195, v80, v195
	v_add_f32_e32 v196, v81, v196
	v_cvt_pk_bf16_f32 v144, v78, v79
	v_cvt_pk_bf16_f32 v145, v80, v81
	s_add_i32 s6, s31, s70
	s_mov_b32 s7, m0
	s_mov_b32 m0, s6
	s_nop 0
	global_load_lds_dwordx4 v197, s[98:99]
	s_mov_b32 m0, s7
	s_add_i32 s6, s76, s71
	s_mov_b32 s7, m0
	s_mov_b32 m0, s6
	s_nop 0
	global_load_lds_dwordx4 v197, s[100:101]
	s_mov_b32 m0, s7
	s_add_u32 s98, s98, 0x2000
	s_addc_u32 s99, s99, 0
	s_add_u32 s100, s100, 0x2000
	s_addc_u32 s101, s101, 0
	s_waitcnt lgkmcnt(14)
	v_mfma_f32_32x32x16_bf16 v[2:17], v[158:161], v[52:55], v[2:17]
	v_exp_f32_e32 v114, v114
	v_exp_f32_e32 v115, v115
	v_exp_f32_e32 v116, v116
	v_exp_f32_e32 v117, v117
	s_waitcnt lgkmcnt(12)
	v_mfma_f32_32x32x16_bf16 v[18:33], v[158:161], v[60:63], v[18:33]
	v_exp_f32_e32 v118, v118
	v_exp_f32_e32 v119, v119
	v_exp_f32_e32 v120, v120
	v_exp_f32_e32 v121, v121
	v_add_u32_e32 v52, s4, v244
	v_add_u32_e32 v198, s25, v245
	ds_read_b128 v[60:63], v52
	ds_read_b128 v[162:165], v52 offset:512
	s_waitcnt lgkmcnt(12)
	v_mfma_f32_32x32x16_bf16 v[2:17], v[154:157], v[82:85], v[2:17]
	v_exp_f32_e32 v122, v122
	v_exp_f32_e32 v123, v123
	v_exp_f32_e32 v124, v124
	v_exp_f32_e32 v125, v125
	ds_read_b128 v[166:169], v52 offset:2048
	ds_read_b128 v[170:173], v52 offset:2560
	s_waitcnt lgkmcnt(12)
	v_mfma_f32_32x32x16_bf16 v[18:33], v[154:157], v[86:89], v[18:33]
	v_exp_f32_e32 v126, v126
	v_exp_f32_e32 v127, v127
	v_exp_f32_e32 v128, v128
	v_exp_f32_e32 v129, v129
	ds_read_b128 v[174:177], v52 offset:4096
	ds_read_b128 v[178:181], v52 offset:4608
	s_waitcnt lgkmcnt(12)
	v_mfma_f32_32x32x16_bf16 v[2:17], v[146:149], v[90:93], v[2:17]
	v_exp_f32_e32 v98, v98
	v_exp_f32_e32 v99, v99
	v_exp_f32_e32 v100, v100
	v_exp_f32_e32 v101, v101
	ds_read_b128 v[182:185], v52 offset:6144
	ds_read_b128 v[52:55], v52 offset:6656
	s_waitcnt lgkmcnt(12)
	v_mfma_f32_32x32x16_bf16 v[18:33], v[146:149], v[64:67], v[18:33]
	v_exp_f32_e32 v102, v102
	v_exp_f32_e32 v103, v103
	v_exp_f32_e32 v104, v104
	v_exp_f32_e32 v105, v105
	s_waitcnt lgkmcnt(10)
	v_mfma_f32_32x32x16_bf16 v[2:17], v[142:145], v[68:71], v[2:17]
	v_exp_f32_e32 v106, v106
	v_exp_f32_e32 v107, v107
	v_exp_f32_e32 v108, v108
	v_exp_f32_e32 v109, v109
	s_waitcnt lgkmcnt(8)
	v_mfma_f32_32x32x16_bf16 v[18:33], v[142:145], v[72:75], v[18:33]
	v_exp_f32_e32 v110, v110
	v_exp_f32_e32 v111, v111
	v_exp_f32_e32 v112, v112
	v_exp_f32_e32 v113, v113
	s_waitcnt vmcnt(2) lgkmcnt(0)
	s_barrier
; #define WAIT_BAR(N) asm volatile("s_waitcnt vmcnt(" #N ") lgkmcnt(0)\n\ts_barrier":::"memory")
;   #define RESC() do{ if(resc){ asm volatile("s_waitcnt lgkmcnt(0)":::"memory"); \
;       _Pragma("unroll") for(int d_=0;d_<2;++d_) _Pragma("unroll") for(int r=0;r<16;++r)o[d_][r]*=wsf[crow(r,hi)]; } }while(0)
;   #define ROT() do{sl_prev=sl_cur;sl_cur=sl_next;sl_next=(sl_next==(NSLOT-1)*SLOTB)?0:sl_next+SLOTB;}while(0)
; template<int THRL> __device__ __forceinline__ void attn_unit(const bf16*Qu,const bf16*__restrict__ Kh,const bf16*__restrict__ Vh,bf16*Ou,const int NT,const float shift,char*shm){
;     ...
;   int t=1;
;     ...
;   for(;t+5<NT;t+=2){
;     STEP(pB0,pB1,pA0,pA1,t,true,true,true);     WAIT_BAR(2); RESC(); ROT();
;     STEP(pA0,pA1,pB0,pB1,t+1,true,true,true);   WAIT_BAR(2); RESC(); ROT();
;   }
	s_add_i32 s6, s76, 0x2000
	s_cmpk_lg_i32 s76, 0x4000
	s_cselect_b32 s31, s6, 0
	ds_read_b64_tr_b16 v[186:187], v198 offset:24576
	ds_read_b64_tr_b16 v[188:189], v198 offset:25088
	s_waitcnt lgkmcnt(9)
	v_mfma_f32_32x32x16_bf16 v[82:97], v[60:63], v[150:153], v[34:49]
	v_add_f32_e32 v50, v114, v50
	v_add_f32_e32 v194, v115, v194
	v_add_f32_e32 v195, v116, v195
	v_add_f32_e32 v196, v117, v196
	v_add_f32_e32 v50, v118, v50
	v_add_f32_e32 v194, v119, v194
	v_cvt_pk_bf16_f32 v158, v114, v115
	v_cvt_pk_bf16_f32 v159, v116, v117
	ds_read_b64_tr_b16 v[60:61], v198 offset:28672
	ds_read_b64_tr_b16 v[62:63], v198 offset:29184
	s_waitcnt lgkmcnt(10)
	v_mfma_f32_32x32x16_bf16 v[66:81], v[162:165], v[150:153], v[34:49]
	v_add_f32_e32 v195, v120, v195
	v_add_f32_e32 v196, v121, v196
	v_add_f32_e32 v50, v122, v50
	v_add_f32_e32 v194, v123, v194
	v_cvt_pk_bf16_f32 v160, v118, v119
	v_cvt_pk_bf16_f32 v161, v120, v121
	ds_read_b64_tr_b16 v[114:115], v198 offset:25600
	ds_read_b64_tr_b16 v[116:117], v198 offset:26112
	s_waitcnt lgkmcnt(11)
	v_mfma_f32_32x32x16_bf16 v[82:97], v[166:169], v[138:141], v[82:97]
	v_add_f32_e32 v195, v124, v195
	v_add_f32_e32 v196, v125, v196
	v_add_f32_e32 v50, v126, v50
	v_add_f32_e32 v194, v127, v194
	v_cvt_pk_bf16_f32 v154, v122, v123
	v_cvt_pk_bf16_f32 v155, v124, v125
	ds_read_b64_tr_b16 v[118:119], v198 offset:29696
	ds_read_b64_tr_b16 v[120:121], v198 offset:30208
	s_waitcnt lgkmcnt(12)
	v_mfma_f32_32x32x16_bf16 v[66:81], v[170:173], v[138:141], v[66:81]
	v_add_f32_e32 v195, v128, v195
	v_add_f32_e32 v196, v129, v196
	v_add_f32_e32 v50, v98, v50
	v_add_f32_e32 v194, v99, v194
	v_cvt_pk_bf16_f32 v156, v126, v127
	v_cvt_pk_bf16_f32 v157, v128, v129
	ds_read_b64_tr_b16 v[122:123], v198 offset:26624
	ds_read_b64_tr_b16 v[124:125], v198 offset:27136
	s_waitcnt lgkmcnt(13)
	v_mfma_f32_32x32x16_bf16 v[82:97], v[174:177], v[134:137], v[82:97]
	v_add_f32_e32 v195, v100, v195
	v_add_f32_e32 v196, v101, v196
	v_add_f32_e32 v50, v102, v50
	v_add_f32_e32 v194, v103, v194
	v_cvt_pk_bf16_f32 v146, v98, v99
	v_cvt_pk_bf16_f32 v147, v100, v101
	ds_read_b64_tr_b16 v[98:99], v198 offset:30720
	ds_read_b64_tr_b16 v[100:101], v198 offset:31232
	s_waitcnt lgkmcnt(14)
	v_mfma_f32_32x32x16_bf16 v[66:81], v[178:181], v[134:137], v[66:81]
	v_add_f32_e32 v195, v104, v195
	v_add_f32_e32 v196, v105, v196
	v_add_f32_e32 v50, v106, v50
	v_add_f32_e32 v194, v107, v194
	v_cvt_pk_bf16_f32 v148, v102, v103
	v_cvt_pk_bf16_f32 v149, v104, v105
	ds_read_b64_tr_b16 v[102:103], v198 offset:27648
	ds_read_b64_tr_b16 v[104:105], v198 offset:28160
	s_waitcnt lgkmcnt(14)
	v_mfma_f32_32x32x16_bf16 v[82:97], v[182:185], v[130:133], v[82:97]
	v_add_f32_e32 v195, v108, v195
	v_add_f32_e32 v196, v109, v196
	v_add_f32_e32 v50, v110, v50
	v_add_f32_e32 v194, v111, v194
	v_cvt_pk_bf16_f32 v142, v106, v107
	v_cvt_pk_bf16_f32 v143, v108, v109
	ds_read_b64_tr_b16 v[106:107], v198 offset:31744
	ds_read_b64_tr_b16 v[108:109], v198 offset:32256
	v_mfma_f32_32x32x16_bf16 v[66:81], v[52:55], v[130:133], v[66:81]
	v_add_f32_e32 v195, v112, v195
	v_add_f32_e32 v196, v113, v196
	v_cvt_pk_bf16_f32 v144, v110, v111
	v_cvt_pk_bf16_f32 v145, v112, v113
	s_add_i32 s6, s76, s70
	s_mov_b32 s7, m0
	s_mov_b32 m0, s6
	s_nop 0
	global_load_lds_dwordx4 v197, s[98:99]
	s_mov_b32 m0, s7
	s_add_i32 s6, s31, s71
	s_mov_b32 s7, m0
	s_mov_b32 m0, s6
	s_nop 0
	global_load_lds_dwordx4 v197, s[100:101]
	s_mov_b32 m0, s7
	s_add_u32 s98, s98, 0x2000
	s_addc_u32 s99, s99, 0
	s_add_u32 s100, s100, 0x2000
	s_addc_u32 s101, s101, 0
	s_waitcnt lgkmcnt(14)
	v_mfma_f32_32x32x16_bf16 v[2:17], v[158:161], v[186:189], v[2:17]
	v_exp_f32_e32 v82, v82
	v_exp_f32_e32 v83, v83
	v_exp_f32_e32 v84, v84
	v_exp_f32_e32 v85, v85
	s_waitcnt lgkmcnt(12)
	v_mfma_f32_32x32x16_bf16 v[18:33], v[158:161], v[60:63], v[18:33]
	v_exp_f32_e32 v86, v86
	v_exp_f32_e32 v87, v87
	v_exp_f32_e32 v88, v88
	v_exp_f32_e32 v89, v89
	v_add_u32_e32 v53, s31, v244
	v_add_u32_e32 v51, s76, v245
	ds_read_b128 v[190:193], v53
	ds_read_b128 v[186:189], v53 offset:512
	s_waitcnt lgkmcnt(12)
	v_mfma_f32_32x32x16_bf16 v[2:17], v[154:157], v[114:117], v[2:17]
	v_exp_f32_e32 v90, v90
	v_exp_f32_e32 v91, v91
	v_exp_f32_e32 v92, v92
	v_exp_f32_e32 v93, v93
	ds_read_b128 v[182:185], v53 offset:2048
	ds_read_b128 v[178:181], v53 offset:2560
	s_waitcnt lgkmcnt(12)
	v_mfma_f32_32x32x16_bf16 v[18:33], v[154:157], v[118:121], v[18:33]
	v_exp_f32_e32 v94, v94
	v_exp_f32_e32 v95, v95
	v_exp_f32_e32 v96, v96
	v_exp_f32_e32 v97, v97
	ds_read_b128 v[174:177], v53 offset:4096
	ds_read_b128 v[170:173], v53 offset:4608
	s_waitcnt lgkmcnt(12)
	v_mfma_f32_32x32x16_bf16 v[2:17], v[146:149], v[122:125], v[2:17]
	v_exp_f32_e32 v66, v66
	v_exp_f32_e32 v67, v67
	v_exp_f32_e32 v68, v68
	v_exp_f32_e32 v69, v69
	ds_read_b128 v[166:169], v53 offset:6144
	ds_read_b128 v[162:165], v53 offset:6656
	s_waitcnt lgkmcnt(12)
	v_mfma_f32_32x32x16_bf16 v[18:33], v[146:149], v[98:101], v[18:33]
	v_exp_f32_e32 v70, v70
	v_exp_f32_e32 v71, v71
	v_exp_f32_e32 v72, v72
	v_exp_f32_e32 v73, v73
	s_waitcnt lgkmcnt(10)
	v_mfma_f32_32x32x16_bf16 v[2:17], v[142:145], v[102:105], v[2:17]
	v_exp_f32_e32 v74, v74
	v_exp_f32_e32 v75, v75
	v_exp_f32_e32 v76, v76
	v_exp_f32_e32 v77, v77
	s_waitcnt lgkmcnt(8)
	v_mfma_f32_32x32x16_bf16 v[18:33], v[142:145], v[106:109], v[18:33]
	v_exp_f32_e32 v78, v78
	v_exp_f32_e32 v79, v79
	v_exp_f32_e32 v80, v80
	v_exp_f32_e32 v81, v81
	s_add_i32 s6, s31, 0x2000
	s_waitcnt vmcnt(2) lgkmcnt(0)
	s_barrier
	s_cmpk_lg_i32 s31, 0x4000
	s_mov_b32 s24, s76
	s_cselect_b32 s76, s6, 0
	s_add_i32 s26, s26, 2
	s_cmp_ge_i32 s26, s91
	s_cbranch_scc0 .LBB0_618
	v_add_f32_e32 v50, v50, v194
	v_add_f32_e32 v50, v50, v195
	v_add_f32_e32 v50, v50, v196
	s_add_i32 s5, s5, -3
	s_branch .LBB0_621
